# LN exchange arrival counters remapped so the 32 panels of one exchange no longer share one cache line (stride 32 B, same 256-word array)
# speedup vs baseline: 1.0127x; 1.0100x over previous
; DI void ln_exchange(const AccT& acc, LAS float* red, float* stats, unsigned* cnt, int pm, int pn, int tid, int wr, int wc, int fr, int fq) {
;     ...
;     float* sp = stats + ((size_t)(pm * 256 + tid) * 8 + pn) * 2;
;     __hip_atomic_store(sp, a, __ATOMIC_RELAXED, __HIP_MEMORY_SCOPE_AGENT); __hip_atomic_store(sp + 1, b, __ATOMIC_RELAXED, __HIP_MEMORY_SCOPE_AGENT); }
;   asm volatile("s_waitcnt vmcnt(0)" ::: "memory");
;   __syncthreads();
;   if (tid == 0) {
;     __builtin_amdgcn_fence(__ATOMIC_RELEASE, "agent");
;     asm volatile("s_waitcnt vmcnt(0)" ::: "memory");
;     __hip_atomic_fetch_add(cnt + pm, 1u, __ATOMIC_RELAXED, __HIP_MEMORY_SCOPE_AGENT);
;     unsigned sp_ = 0;
;     while (__hip_atomic_load(cnt + pm, __ATOMIC_RELAXED, __HIP_MEMORY_SCOPE_AGENT) < 8u) { __builtin_amdgcn_s_sleep(1); if (++sp_ > (1u << 24)) break; }
.LBB0_1803:
	s_or_b64 exec, exec, s[4:5]
	v_readlane_b32 s4, v252, 29
	s_lshl_b32 s72, s4, 2
	s_lshl_b64 s[4:5], s[72:73], 2
	v_readlane_b32 s9, v251, 30
	s_waitcnt vmcnt(0)
	s_add_u32 s24, s9, s4
	v_readlane_b32 s4, v251, 31
	s_addc_u32 s25, s4, s5
	v_cmp_eq_u32_e64 s[4:5], 0, v166
	s_barrier
	s_and_saveexec_b64 s[14:15], s[4:5]
	s_cbranch_execz .LBB0_1820
	s_mov_b64 s[18:19], exec
	s_ashr_i32 s9, s8, 31
	s_waitcnt vmcnt(0)
	s_waitcnt vmcnt(0)
	s_lshl_b64 s[16:17], s[8:9], 5
	v_mbcnt_lo_u32_b32 v130, s18, 0
	s_add_u32 s16, s24, s16
	v_mbcnt_hi_u32_b32 v130, s19, v130
	s_addc_u32 s17, s25, s17
	v_cmp_eq_u32_e32 vcc, 0, v130
	s_and_saveexec_b64 s[20:21], vcc
	s_cbranch_execz .LBB0_1806
	s_bcnt1_i32_b64 s9, s[18:19]
	v_mov_b32_e32 v130, s9
	global_atomic_add v1, v130, s[16:17]

; DI void ln_exchange(const AccT& acc, LAS float* red, float* stats, unsigned* cnt, int pm, int pn, int tid, int wr, int wc, int fr, int fq) {
;     ...
;     float* sp = stats + ((size_t)(pm * 256 + tid) * 8 + pn) * 2;
;     __hip_atomic_store(sp, a, __ATOMIC_RELAXED, __HIP_MEMORY_SCOPE_AGENT); __hip_atomic_store(sp + 1, b, __ATOMIC_RELAXED, __HIP_MEMORY_SCOPE_AGENT); }
;   asm volatile("s_waitcnt vmcnt(0)" ::: "memory");
;   __syncthreads();
;   if (tid == 0) {
;     __builtin_amdgcn_fence(__ATOMIC_RELEASE, "agent");
;     asm volatile("s_waitcnt vmcnt(0)" ::: "memory");
;     __hip_atomic_fetch_add(cnt + pm, 1u, __ATOMIC_RELAXED, __HIP_MEMORY_SCOPE_AGENT);
;     unsigned sp_ = 0;
;     while (__hip_atomic_load(cnt + pm, __ATOMIC_RELAXED, __HIP_MEMORY_SCOPE_AGENT) < 8u) { __builtin_amdgcn_s_sleep(1); if (++sp_ > (1u << 24)) break; }
.LBB0_1840:
	s_or_b64 exec, exec, s[0:1]
	s_waitcnt vmcnt(0)
	s_barrier
	s_and_saveexec_b64 s[0:1], s[4:5]
	s_cbranch_execz .LBB0_1857
	s_ashr_i32 s9, s8, 31
	s_lshl_b64 s[4:5], s[8:9], 5
	s_mov_b64 s[8:9], exec
	s_waitcnt vmcnt(0)
	s_waitcnt vmcnt(0)
	v_mbcnt_lo_u32_b32 v0, s8, 0
	s_add_u32 s4, s24, s4
	v_mbcnt_hi_u32_b32 v0, s9, v0
	s_addc_u32 s5, s25, s5
	v_cmp_eq_u32_e32 vcc, 0, v0
	s_and_saveexec_b64 s[10:11], vcc
	s_cbranch_execz .LBB0_1843
	s_bcnt1_i32_b64 s8, s[8:9]
	v_mov_b32_e32 v0, s8
	global_atomic_add v1, v0, s[4:5] offset:4

; DI void ln_exchange(const AccT& acc, LAS float* red, float* stats, unsigned* cnt, int pm, int pn, int tid, int wr, int wc, int fr, int fq) {
;     ...
;     while (__hip_atomic_load(cnt + pm, __ATOMIC_RELAXED, __HIP_MEMORY_SCOPE_AGENT) < 8u) { __builtin_amdgcn_s_sleep(1); if (++sp_ > (1u << 24)) break; }
.LBB0_1846:
	global_load_dword v0, v1, s[4:5] offset:4 sc1
	s_mov_b64 s[8:9], -1
	s_waitcnt vmcnt(0)
	v_cmp_lt_u32_e32 vcc, 7, v0
	s_cbranch_vccnz .LBB0_1845
	s_cmp_lg_u32 s10, 0
	s_sleep 1
	s_cbranch_scc0 .LBB0_1844
	global_load_dword v0, v1, s[4:5] offset:4 sc1
	s_waitcnt vmcnt(0)
	v_cmp_gt_u32_e32 vcc, 8, v0
	s_cbranch_vccz .LBB0_1845
	s_sleep 1
	global_load_dword v0, v1, s[4:5] offset:4 sc1
	s_waitcnt vmcnt(0)
	v_cmp_gt_u32_e32 vcc, 8, v0
	s_cbranch_vccz .LBB0_1845
	s_sleep 1
	global_load_dword v0, v1, s[4:5] offset:4 sc1
	s_waitcnt vmcnt(0)
	v_cmp_gt_u32_e32 vcc, 8, v0
	s_cbranch_vccz .LBB0_1845
	s_sleep 1
	global_load_dword v0, v1, s[4:5] offset:4 sc1
	s_waitcnt vmcnt(0)
	v_cmp_gt_u32_e32 vcc, 8, v0
	s_cbranch_vccz .LBB0_1845
	s_sleep 1
	global_load_dword v0, v1, s[4:5] offset:4 sc1
	s_waitcnt vmcnt(0)
	v_cmp_gt_u32_e32 vcc, 8, v0
	s_cbranch_vccz .LBB0_1845
	s_sleep 1
	global_load_dword v0, v1, s[4:5] offset:4 sc1
	s_waitcnt vmcnt(0)
	v_cmp_gt_u32_e32 vcc, 8, v0
	s_cbranch_vccz .LBB0_1845
	s_sleep 1
	global_load_dword v0, v1, s[4:5] offset:4 sc1
	s_waitcnt vmcnt(0)
	v_cmp_gt_u32_e32 vcc, 8, v0
	s_cbranch_vccz .LBB0_1845
	s_sleep 1
	s_add_i32 s10, s10, -8
	s_mov_b64 s[8:9], 0
	s_branch .LBB0_1845

; DI void ln_exchange(const AccT& acc, LAS float* red, float* stats, unsigned* cnt, int pm, int pn, int tid, int wr, int wc, int fr, int fq) {
;     ...
;     float* sp = stats + ((size_t)(pm * 256 + tid) * 8 + pn) * 2;
;     __hip_atomic_store(sp, a, __ATOMIC_RELAXED, __HIP_MEMORY_SCOPE_AGENT); __hip_atomic_store(sp + 1, b, __ATOMIC_RELAXED, __HIP_MEMORY_SCOPE_AGENT); }
;   asm volatile("s_waitcnt vmcnt(0)" ::: "memory");
;   __syncthreads();
;   if (tid == 0) {
;     __builtin_amdgcn_fence(__ATOMIC_RELEASE, "agent");
;     asm volatile("s_waitcnt vmcnt(0)" ::: "memory");
;     __hip_atomic_fetch_add(cnt + pm, 1u, __ATOMIC_RELAXED, __HIP_MEMORY_SCOPE_AGENT);
;     unsigned sp_ = 0;
;     while (__hip_atomic_load(cnt + pm, __ATOMIC_RELAXED, __HIP_MEMORY_SCOPE_AGENT) < 8u) { __builtin_amdgcn_s_sleep(1); if (++sp_ > (1u << 24)) break; }
.LBB0_2016:
	s_or_b64 exec, exec, s[4:5]
	s_lshl_b32 s72, s6, 1
	s_lshl_b64 s[4:5], s[72:73], 2
	v_readlane_b32 s9, v251, 30
	s_waitcnt vmcnt(0)
	s_add_u32 s25, s9, s4
	v_readlane_b32 s4, v251, 31
	s_addc_u32 s26, s4, s5
	v_cmp_eq_u32_e64 s[4:5], 0, v220
	s_barrier
	s_and_saveexec_b64 s[14:15], s[4:5]
	s_cbranch_execz .LBB0_2033
	s_mov_b64 s[18:19], exec
	s_ashr_i32 s9, s8, 31
	s_waitcnt vmcnt(0)
	s_waitcnt vmcnt(0)
	s_lshl_b64 s[16:17], s[8:9], 5
	v_mbcnt_lo_u32_b32 v130, s18, 0
	s_add_u32 s16, s25, s16
	v_mbcnt_hi_u32_b32 v130, s19, v130
	s_addc_u32 s17, s26, s17
	v_cmp_eq_u32_e32 vcc, 0, v130
	s_and_saveexec_b64 s[20:21], vcc
	s_cbranch_execz .LBB0_2019
	s_bcnt1_i32_b64 s9, s[18:19]
	v_mov_b32_e32 v130, s9
	global_atomic_add v1, v130, s[16:17]

; DI void ln_exchange(const AccT& acc, LAS float* red, float* stats, unsigned* cnt, int pm, int pn, int tid, int wr, int wc, int fr, int fq) {
;     ...
;     float* sp = stats + ((size_t)(pm * 256 + tid) * 8 + pn) * 2;
;     __hip_atomic_store(sp, a, __ATOMIC_RELAXED, __HIP_MEMORY_SCOPE_AGENT); __hip_atomic_store(sp + 1, b, __ATOMIC_RELAXED, __HIP_MEMORY_SCOPE_AGENT); }
;   asm volatile("s_waitcnt vmcnt(0)" ::: "memory");
;   __syncthreads();
;   if (tid == 0) {
;     __builtin_amdgcn_fence(__ATOMIC_RELEASE, "agent");
;     asm volatile("s_waitcnt vmcnt(0)" ::: "memory");
;     __hip_atomic_fetch_add(cnt + pm, 1u, __ATOMIC_RELAXED, __HIP_MEMORY_SCOPE_AGENT);
;     unsigned sp_ = 0;
;     while (__hip_atomic_load(cnt + pm, __ATOMIC_RELAXED, __HIP_MEMORY_SCOPE_AGENT) < 8u) { __builtin_amdgcn_s_sleep(1); if (++sp_ > (1u << 24)) break; }
.LBB0_2054:
	s_or_b64 exec, exec, s[0:1]
	s_waitcnt vmcnt(0)
	s_barrier
	s_and_saveexec_b64 s[0:1], s[4:5]
	s_cbranch_execz .LBB0_2071
	s_ashr_i32 s9, s8, 31
	s_mov_b64 s[6:7], exec
	s_waitcnt vmcnt(0)
	s_waitcnt vmcnt(0)
	s_lshl_b64 s[4:5], s[8:9], 5
	v_mbcnt_lo_u32_b32 v0, s6, 0
	s_add_u32 s4, s25, s4
	v_mbcnt_hi_u32_b32 v0, s7, v0
	s_addc_u32 s5, s26, s5
	v_cmp_eq_u32_e32 vcc, 0, v0
	s_and_saveexec_b64 s[8:9], vcc
	s_cbranch_execz .LBB0_2057
	s_bcnt1_i32_b64 s6, s[6:7]
	v_mov_b32_e32 v0, s6
	global_atomic_add v1, v0, s[4:5] offset:4

; DI void ln_exchange(const AccT& acc, LAS float* red, float* stats, unsigned* cnt, int pm, int pn, int tid, int wr, int wc, int fr, int fq) {
;     ...
;     while (__hip_atomic_load(cnt + pm, __ATOMIC_RELAXED, __HIP_MEMORY_SCOPE_AGENT) < 8u) { __builtin_amdgcn_s_sleep(1); if (++sp_ > (1u << 24)) break; }
.LBB0_2060:
	global_load_dword v0, v1, s[4:5] offset:4 sc1
	s_mov_b64 s[6:7], -1
	s_waitcnt vmcnt(0)
	v_cmp_lt_u32_e32 vcc, 7, v0
	s_cbranch_vccnz .LBB0_2059
	s_cmp_lg_u32 s8, 0
	s_sleep 1
	s_cbranch_scc0 .LBB0_2058
	global_load_dword v0, v1, s[4:5] offset:4 sc1
	s_waitcnt vmcnt(0)
	v_cmp_gt_u32_e32 vcc, 8, v0
	s_cbranch_vccz .LBB0_2059
	s_sleep 1
	global_load_dword v0, v1, s[4:5] offset:4 sc1
	s_waitcnt vmcnt(0)
	v_cmp_gt_u32_e32 vcc, 8, v0
	s_cbranch_vccz .LBB0_2059
	s_sleep 1
	global_load_dword v0, v1, s[4:5] offset:4 sc1
	s_waitcnt vmcnt(0)
	v_cmp_gt_u32_e32 vcc, 8, v0
	s_cbranch_vccz .LBB0_2059
	s_sleep 1
	global_load_dword v0, v1, s[4:5] offset:4 sc1
	s_waitcnt vmcnt(0)
	v_cmp_gt_u32_e32 vcc, 8, v0
	s_cbranch_vccz .LBB0_2059
	s_sleep 1
	global_load_dword v0, v1, s[4:5] offset:4 sc1
	s_waitcnt vmcnt(0)
	v_cmp_gt_u32_e32 vcc, 8, v0
	s_cbranch_vccz .LBB0_2059
	s_sleep 1
	global_load_dword v0, v1, s[4:5] offset:4 sc1
	s_waitcnt vmcnt(0)
	v_cmp_gt_u32_e32 vcc, 8, v0
	s_cbranch_vccz .LBB0_2059
	s_sleep 1
	global_load_dword v0, v1, s[4:5] offset:4 sc1
	s_waitcnt vmcnt(0)
	v_cmp_gt_u32_e32 vcc, 8, v0
	s_cbranch_vccz .LBB0_2059
	s_sleep 1
	s_add_i32 s8, s8, -8
	s_mov_b64 s[6:7], 0
	s_branch .LBB0_2059
